# adds: the 8 K-fragment ds_reads moved from the exposed loop top into the PV MFMA1-5 gaps (wait before QK is lgkmcnt(5)), MFMA1 issues right after the barrier
# speedup vs baseline: 1.0240x; 1.0240x over previous
; #define MFMA32(a, b, c) __builtin_amdgcn_mfma_f32_32x32x16_bf16((a), (b), (c), 0, 0, 0)
; #define VLOAD(dst, sbv, q) do { _Pragma("unroll") for (int d_ = 0; d_ < 4; ++d_) dst[d_] = *(const lds_bf16x8*)((sbv) + vo[q] + d_ * 4096); } while (0)
; #define FENCE __builtin_amdgcn_sched_barrier(0)
; DI void diff_unit(KP p, int l, int b, int h, int qb, int isctx, float lamv, float lam_init, char* ldsc) {
;     ...
;   for (int kt = 0; kt < nt - 1; ++kt) {
;     asm volatile("s_waitcnt vmcnt(0)" ::: "memory");
;     __builtin_amdgcn_s_barrier();
;     const int stg1 = stg == 2 ? 0 : stg + 1;
;     if (kt + 2 < nt) { const int s2_ = stg >= 1 ? stg - 1 : 2; DISSUE(kt + 2, s2_); }
;     if (need) {
; #pragma unroll
;       for (int d = 0; d < 4; ++d) o[d] *= alpha;
;     }
;     const lds_u8* sbv = L + stg * STG + 16384;
;     const lds_u8* sbk = L + stg1 * STG + comp * 8192;
;     bf16x8 kf[2][4];
;     f32x16 st[2];
; #pragma unroll
;     for (int t = 0; t < 2; ++t)
; #pragma unroll
;       for (int ks = 0; ks < 4; ++ks) kf[t][ks] = *(const lds_bf16x8*)(sbk + ko[ks] + t * 4096);
;     FENCE;
;     pv_grp(o, vA, P[0]); pv_grp(o, vB, P[1]);
;     VLOAD(vA, sbv, 2); VLOAD(vB, sbv, 3);
;     FENCE;
; #pragma unroll
;     for (int i = 0; i < 16; ++i) { st[0][i] = 0.f; st[1][i] = 0.f; }
; #pragma unroll
;     for (int ks = 0; ks < 4; ++ks) st[0] = MFMA32(kf[0][ks], qf[ks], st[0]);
; #pragma unroll
;     for (int ks = 0; ks < 4; ++ks) st[1] = MFMA32(kf[1][ks], qf[ks], st[1]);
;     FENCE;
.LBB0_475:
.LBB0_477:
	s_waitcnt lgkmcnt(0)
	v_mfma_f32_32x32x16_bf16 v[50:65], v[86:89], v[66:69], v[50:65]
	s_add_i32 s2, s17, 1
	s_and_b32 s16, s2, 3
	s_lshl_b32 s15, s16, 15
	ds_read_b128 v[220:223], v248 offset:24576
	ds_read_b128 v[224:227], v248 offset:28672
	ds_read_b128 v[154:157], v136
	ds_read_b128 v[192:195], v136 offset:4096
	v_mfma_f32_32x32x16_bf16 v[34:49], v[82:85], v[66:69], v[34:49]
	v_cvt_pk_bf16_f32 v118, v228, v229
	v_cvt_pk_bf16_f32 v119, v230, v231
	v_cvt_pk_bf16_f32 v120, v232, v233
	v_cvt_pk_bf16_f32 v121, v234, v235
	ds_read_b128 v[196:199], v137
	v_mfma_f32_32x32x16_bf16 v[18:33], v[78:81], v[66:69], v[18:33]
	v_cvt_pk_bf16_f32 v114, v236, v237
	v_cvt_pk_bf16_f32 v115, v238, v239
	v_cvt_pk_bf16_f32 v116, v240, v241
	v_cvt_pk_bf16_f32 v117, v242, v243
	ds_read_b128 v[200:203], v137 offset:4096
	v_mfma_f32_32x32x16_bf16 v[2:17], v[74:77], v[66:69], v[2:17]
	v_mov_b64_e32 v[66:67], v[252:253]
	v_mov_b64_e32 v[68:69], v[252:253]
	v_mov_b64_e32 v[74:75], v[252:253]
	ds_read_b128 v[204:207], v138
	ds_read_b128 v[208:211], v138 offset:4096
	v_mfma_f32_32x32x16_bf16 v[50:65], v[126:129], v[70:73], v[50:65]
	v_mov_b64_e32 v[76:77], v[252:253]
	v_mov_b64_e32 v[78:79], v[252:253]
	v_mov_b64_e32 v[80:81], v[252:253]
	ds_read_b128 v[126:129], v248 offset:20480
	ds_read_b128 v[212:215], v139
	ds_read_b128 v[216:219], v139 offset:4096
	v_mfma_f32_32x32x16_bf16 v[34:49], v[122:125], v[70:73], v[34:49]
	ds_read_b128 v[122:125], v248 offset:16384
	ds_read_b128 v[228:231], v255 offset:16384
	ds_read_b128 v[232:235], v255 offset:20480
	v_mfma_f32_32x32x16_bf16 v[18:33], v[94:97], v[70:73], v[18:33]
	ds_read_b128 v[236:239], v255 offset:24576
	ds_read_b128 v[240:243], v255 offset:28672
	v_mfma_f32_32x32x16_bf16 v[2:17], v[90:93], v[70:73], v[2:17]
	v_mov_b64_e32 v[70:71], v[252:253]
	v_mov_b64_e32 v[72:73], v[252:253]
	s_add_i32 s18, s3, 0xc0
	s_add_i32 s19, s10, 64
	s_cmp_eq_u32 s11, 0
	s_cselect_b32 s19, s18, s19
	s_waitcnt lgkmcnt(5)
	v_mfma_f32_32x32x16_bf16 v[82:97], v[154:157], v[98:101], v[66:81]
	s_add_i32 s11, s11, 1
	s_add_i32 s10, s10, 64
	s_mul_i32 s19, s19, 0x1600
	s_add_u32 s18, s22, s19
	s_addc_u32 s19, s23, 0
	v_mfma_f32_32x32x16_bf16 v[66:81], v[192:195], v[98:101], v[66:81]
	s_add_i32 s24, s17, 3
	s_and_b32 s24, s24, 3
	s_lshl_b32 s24, s24, 15
	s_add_i32 s24, s13, s24
	s_mov_b32 m0, s24
	v_mfma_f32_32x32x16_bf16 v[66:81], v[200:203], v[102:105], v[66:81]
	global_load_lds_dwordx4 v244, s[18:19]
	s_add_i32 m0, s24, 0x2000
	v_mfma_f32_32x32x16_bf16 v[82:97], v[196:199], v[102:105], v[82:97]
	global_load_lds_dwordx4 v245, s[18:19]
	s_add_i32 m0, s24, 0x4000
	v_mfma_f32_32x32x16_bf16 v[66:81], v[208:211], v[106:109], v[66:81]
	global_load_lds_dwordx4 v246, s[20:21]
	s_add_i32 m0, s24, 0x6000
	v_mfma_f32_32x32x16_bf16 v[82:97], v[204:207], v[106:109], v[82:97]
	global_load_lds_dwordx4 v247, s[20:21]
	s_add_u32 s20, s20, 0x80
	s_addc_u32 s21, s21, 0
	v_mfma_f32_32x32x16_bf16 v[66:81], v[216:219], v[110:113], v[66:81]
	s_add_i32 s18, s16, 1
	s_and_b32 s18, s18, 3
	s_lshl_b32 s18, s18, 15
	s_add_i32 s18, s18, s14
	v_add_u32_e32 v251, s15, v150
	v_add_u32_e32 v249, s15, v151
	v_mfma_f32_32x32x16_bf16 v[82:97], v[212:215], v[110:113], v[82:97]
	v_add_u32_e32 v136, s18, v141
	v_add_u32_e32 v137, s18, v145
	v_add_u32_e32 v138, s18, v147
	v_add_u32_e32 v139, s18, v148
	v_add_u32_e32 v248, s15, v149
	v_add_u32_e32 v255, s15, v146
	s_waitcnt lgkmcnt(0)
	v_mfma_f32_32x32x16_bf16 v[50:65], v[122:125], v[118:121], v[50:65]
	s_mov_b32 s17, s16
	s_cmpk_lg_i32 s11, 0x83
	v_mfma_f32_32x32x16_bf16 v[34:49], v[126:129], v[118:121], v[34:49]
	s_nop 0
	v_exp_f32_e32 v122, v82
	v_exp_f32_e32 v124, v83
	v_exp_f32_e32 v126, v84
	v_exp_f32_e32 v128, v85
	v_exp_f32_e32 v156, v86
	v_mfma_f32_32x32x16_bf16 v[18:33], v[220:223], v[118:121], v[18:33]
	v_exp_f32_e32 v192, v87
	v_exp_f32_e32 v194, v88
	v_exp_f32_e32 v196, v89
	v_exp_f32_e32 v123, v90
	v_exp_f32_e32 v125, v91
	v_mfma_f32_32x32x16_bf16 v[2:17], v[224:227], v[118:121], v[2:17]
	v_exp_f32_e32 v127, v92
	v_exp_f32_e32 v129, v93
	v_exp_f32_e32 v157, v94
	v_exp_f32_e32 v193, v95
	v_exp_f32_e32 v195, v96
	v_mfma_f32_32x32x16_bf16 v[50:65], v[228:231], v[114:117], v[50:65]
	v_exp_f32_e32 v197, v97
	v_exp_f32_e32 v228, v66
	v_exp_f32_e32 v229, v67
	v_exp_f32_e32 v230, v68
	v_exp_f32_e32 v231, v69
	v_mfma_f32_32x32x16_bf16 v[34:49], v[232:235], v[114:117], v[34:49]
	v_exp_f32_e32 v232, v70
	v_exp_f32_e32 v233, v71
	v_exp_f32_e32 v234, v72
	v_exp_f32_e32 v235, v73
	v_pk_add_f32 v[92:93], v[124:125], v[122:123]
	v_pk_add_f32 v[92:93], v[126:127], v[92:93]
	v_mfma_f32_32x32x16_bf16 v[18:33], v[236:239], v[114:117], v[18:33]
	v_exp_f32_e32 v236, v74
	v_exp_f32_e32 v237, v75
	v_exp_f32_e32 v238, v76
	v_exp_f32_e32 v239, v77
	v_pk_add_f32 v[92:93], v[128:129], v[92:93]
	v_pk_add_f32 v[92:93], v[156:157], v[92:93]
	v_mfma_f32_32x32x16_bf16 v[2:17], v[240:243], v[114:117], v[2:17]
	v_exp_f32_e32 v240, v78
	v_exp_f32_e32 v241, v79
	v_exp_f32_e32 v242, v80
	v_exp_f32_e32 v243, v81
	v_pk_add_f32 v[92:93], v[192:193], v[92:93]
	v_pk_add_f32 v[92:93], v[194:195], v[92:93]
	v_pk_add_f32 v[92:93], v[196:197], v[92:93]
	ds_read_b128 v[78:81], v251 offset:24576
	ds_read_b128 v[74:77], v251 offset:28672
	v_pk_add_f32 v[198:199], v[228:229], v[230:231]
	v_pk_add_f32 v[198:199], v[232:233], v[198:199]
	v_pk_add_f32 v[198:199], v[234:235], v[198:199]
	v_pk_add_f32 v[198:199], v[236:237], v[198:199]
	v_pk_add_f32 v[198:199], v[238:239], v[198:199]
	v_pk_add_f32 v[198:199], v[240:241], v[198:199]
	v_pk_add_f32 v[198:199], v[242:243], v[198:199]
	v_pk_add_f32 v[198:199], v[198:199], v[92:93]
	v_max_f32_e32 v200, v198, v199
	v_cmp_lt_f32_e32 vcc, 0x43000000, v200
	s_cbranch_vccnz .Ldiff_rare
